# v37 + rmsnorm+mod copy at LBB0_1907: all 16 row loads hoisted to the top with counted vmcnt
# baseline (speedup 1.0000x reference)
;     ...
;     for (int r = rbeg + gw; r < nrows; r += nw) {
;         const float* xp = (r < T_LAT) ? xlat + (size_t)r * DM : xctx + (size_t)(r - T_LAT) * DM;
;         const int m = (r < T_LAT) ? (r >> 12) : 8;
;         const float* mv = p.modv + ((size_t)layer * 9 + m) * 6144 + shift_i * 1024;
;         f32x4 v[4];
;         float ss = 0.f;
; #pragma unroll
;         for (int i = 0; i < 4; ++i) {
;             v[i] = *reinterpret_cast<const f32x4*>(xp + (i * 64 + lane) * 4);
;             ss += v[i][0] * v[i][0] + v[i][1] * v[i][1] + v[i][2] * v[i][2] + v[i][3] * v[i][3];
;         }
; #pragma unroll
;         for (int o = 32; o >= 1; o >>= 1) ss += __shfl_xor(ss, o);
;         const float rstd = rsqrtf(ss * (1.0f / 1024.0f) + EPSV);
;         bf16_t* hp = p.hbuf + (size_t)r * DM;
; #pragma unroll
;         for (int i = 0; i < 4; ++i) {
;             const int col = (i * 64 + lane) * 4;
;             f32x4 gg = *reinterpret_cast<const f32x4*>(g + col);
;             f32x4 sh = *reinterpret_cast<const f32x4*>(mv + col);
;             f32x4 sc = *reinterpret_cast<const f32x4*>(mv + 1024 + col);
;             float o0 = v[i][0] * rstd * gg[0] * (1.f + sc[0]) + sh[0];
;             float o1 = v[i][1] * rstd * gg[1] * (1.f + sc[1]) + sh[1];
;             float o2 = v[i][2] * rstd * gg[2] * (1.f + sc[2]) + sh[2];
;             float o3 = v[i][3] * rstd * gg[3] * (1.f + sc[3]) + sh[3];
;             u32x2 o = {pack2(o0, o1), pack2(o2, o3)};
;             *reinterpret_cast<u32x2*>(hp + col) = o;
;         }
;     }
.LBB0_1907:
	s_or_b64 exec, exec, s[14:15]
	v_mov_b32_e32 v33, v0
	v_lshl_add_u64 v[2:3], v[2:3], 0, v[32:33]
	global_load_dwordx4 v[14:17], v[2:3], off
	global_load_dwordx4 v[10:13], v[2:3], off offset:1024
	global_load_dwordx4 v[192:195], v[2:3], off offset:2048
	global_load_dwordx4 v[196:199], v[2:3], off offset:3072
	global_load_dwordx4 v[200:203], v[24:25], off
	global_load_dwordx4 v[204:207], v[24:25], off offset:1024
	global_load_dwordx4 v[208:211], v[24:25], off offset:2048
	global_load_dwordx4 v[212:215], v[24:25], off offset:3072
	v_min_i32_e32 v4, 0x8000, v4
	v_ashrrev_i32_e32 v4, 12, v4
	v_readlane_b32 s44, v254, 6
	v_ashrrev_i32_e32 v5, 31, v4
	v_readlane_b32 s50, v254, 12
	v_readlane_b32 s51, v254, 13
	v_lshl_add_u64 v[4:5], v[4:5], 0, s[20:21]
	v_mov_b32_e32 v37, v0
	v_mov_b64_e32 v[6:7], s[50:51]
	v_mad_u64_u32 v[18:19], s[0:1], v4, s74, v[6:7]
	v_mad_i32_i24 v19, v5, s74, v19
	v_mov_b32_e32 v39, v0
	v_mov_b32_e32 v242, v34
	v_mov_b32_e32 v243, v0
	v_lshl_add_u64 v[240:241], v[18:19], 0, v[32:33]
	v_lshl_add_u64 v[248:249], v[18:19], 0, s[90:91]
	global_load_dwordx4 v[216:219], v[240:241], off
	global_load_dwordx4 v[220:223], v[240:241], off offset:1024
	global_load_dwordx4 v[224:227], v[240:241], off offset:2048
	global_load_dwordx4 v[228:231], v[240:241], off offset:3072
	v_lshl_add_u64 v[240:241], v[248:249], 0, v[32:33]
	global_load_dwordx4 v[56:59], v[240:241], off
	v_lshl_add_u64 v[240:241], v[248:249], 0, v[242:243]
	global_load_dwordx4 v[232:235], v[240:241], off
	v_lshl_add_u64 v[240:241], v[248:249], 0, v[36:37]
	global_load_dwordx4 v[236:239], v[240:241], off
	v_lshl_add_u64 v[240:241], v[248:249], 0, v[38:39]
	global_load_dwordx4 v[244:247], v[240:241], off
	v_add_u32_e32 v28, s38, v28
	v_lshl_add_u64 v[22:23], v[22:23], 0, s[38:39]
	v_lshl_add_u64 v[30:31], v[30:31], 0, s[52:53]
	v_readlane_b32 s45, v254, 7
	v_readlane_b32 s46, v254, 8
	v_readlane_b32 s47, v254, 9
	v_readlane_b32 s48, v254, 10
	v_readlane_b32 s49, v254, 11
	s_waitcnt vmcnt(14)
	v_mov_b32_e32 v6, v15
	v_mov_b32_e32 v7, v11
	v_mov_b32_e32 v4, v14
	v_mov_b32_e32 v5, v10
	v_pk_mul_f32 v[6:7], v[6:7], v[6:7]
	s_nop 0
	v_pk_fma_f32 v[4:5], v[4:5], v[4:5], v[6:7]
	v_mov_b32_e32 v6, v16
	v_mov_b32_e32 v7, v12
	v_pk_fma_f32 v[4:5], v[6:7], v[6:7], v[4:5]
	v_mov_b32_e32 v6, v17
	v_mov_b32_e32 v7, v13
	v_pk_fma_f32 v[42:43], v[6:7], v[6:7], v[4:5]
	s_waitcnt vmcnt(12)
	v_mov_b32_e32 v6, v192
	v_mov_b32_e32 v7, v193
	v_mov_b32_e32 v8, v194
	v_mov_b32_e32 v9, v195
	v_mov_b32_e32 v2, v196
	v_mov_b32_e32 v3, v197
	v_mov_b32_e32 v4, v198
	v_mov_b32_e32 v5, v199
	v_add_f32_e32 v29, v42, v43
	v_lshlrev_b64 v[42:43], 11, v[20:21]
	v_lshl_add_u64 v[42:43], v[26:27], 0, v[42:43]
	v_mov_b32_e32 v46, v7
	v_mov_b32_e32 v47, v3
	v_mov_b32_e32 v44, v6
	v_mov_b32_e32 v45, v2
	v_pk_mul_f32 v[46:47], v[46:47], v[46:47]
	s_nop 0
	v_pk_fma_f32 v[44:45], v[44:45], v[44:45], v[46:47]
	v_mov_b32_e32 v46, v8
	v_mov_b32_e32 v47, v4
	v_pk_fma_f32 v[44:45], v[46:47], v[46:47], v[44:45]
	v_mov_b32_e32 v46, v9
	v_mov_b32_e32 v47, v5
	v_pk_fma_f32 v[44:45], v[46:47], v[46:47], v[44:45]
	s_nop 0
	v_add_f32_e32 v29, v29, v44
	v_add_f32_e32 v29, v29, v45
	ds_bpermute_b32 v35, v1, v29
	s_waitcnt lgkmcnt(0)
	v_add_f32_e32 v29, v29, v35
	ds_bpermute_b32 v35, v41, v29
	s_waitcnt lgkmcnt(0)
	v_add_f32_e32 v29, v29, v35
	ds_bpermute_b32 v35, v48, v29
	s_waitcnt lgkmcnt(0)
	v_add_f32_e32 v29, v29, v35
	ds_bpermute_b32 v35, v49, v29
	s_waitcnt lgkmcnt(0)
	v_add_f32_e32 v29, v29, v35
	ds_bpermute_b32 v35, v50, v29
	s_waitcnt lgkmcnt(0)
	v_add_f32_e32 v29, v29, v35
	ds_bpermute_b32 v35, v51, v29
	s_waitcnt lgkmcnt(0)
	v_add_f32_e32 v29, v29, v35
	v_fmamk_f32 v29, v29, 0x3a800000, v177
	v_cmp_gt_f32_e32 vcc, s93, v29
	v_mul_f32_e32 v35, 0x4b800000, v29
	s_nop 0
	v_cndmask_b32_e32 v29, v29, v35, vcc
	v_rsq_f32_e32 v29, v29
	s_nop 0
	v_mul_f32_e32 v35, 0x45800000, v29
	v_cndmask_b32_e32 v40, v29, v35, vcc
	v_pk_mul_f32 v[14:15], v[14:15], v[40:41] op_sel_hi:[1,0]
	v_pk_mul_f32 v[16:17], v[16:17], v[40:41] op_sel_hi:[1,0]
	v_mov_b32_e32 v35, v0
	v_pk_mul_f32 v[10:11], v[10:11], v[40:41] op_sel_hi:[1,0]
	v_pk_mul_f32 v[12:13], v[12:13], v[40:41] op_sel_hi:[1,0]
	v_pk_mul_f32 v[6:7], v[6:7], v[40:41] op_sel_hi:[1,0]
	v_pk_mul_f32 v[8:9], v[8:9], v[40:41] op_sel_hi:[1,0]
	v_pk_mul_f32 v[2:3], v[2:3], v[40:41] op_sel_hi:[1,0]
	v_pk_mul_f32 v[4:5], v[4:5], v[40:41] op_sel_hi:[1,0]
	s_waitcnt vmcnt(0)
	v_pk_mul_f32 v[14:15], v[200:201], v[14:15]
	v_pk_mul_f32 v[16:17], v[202:203], v[16:17]
	v_pk_add_f32 v[52:53], v[56:57], 1.0 op_sel_hi:[1,0]
	s_nop 0
	v_pk_fma_f32 v[14:15], v[52:53], v[14:15], v[216:217]
	v_pk_add_f32 v[18:19], v[58:59], 1.0 op_sel_hi:[1,0]
	v_cvt_pk_bf16_f32 v14, v14, v15
	v_pk_fma_f32 v[16:17], v[18:19], v[16:17], v[218:219]
	v_pk_mul_f32 v[10:11], v[204:205], v[10:11]
	v_cvt_pk_bf16_f32 v15, v16, v17
	global_store_dwordx2 v[42:43], v[14:15], off
	v_pk_mul_f32 v[12:13], v[206:207], v[12:13]
	v_pk_add_f32 v[18:19], v[232:233], 1.0 op_sel_hi:[1,0]
	s_nop 0
	v_pk_fma_f32 v[10:11], v[18:19], v[10:11], v[220:221]
	v_pk_add_f32 v[14:15], v[234:235], 1.0 op_sel_hi:[1,0]
	v_cvt_pk_bf16_f32 v10, v10, v11
	v_pk_fma_f32 v[12:13], v[14:15], v[12:13], v[222:223]
	v_pk_mul_f32 v[6:7], v[208:209], v[6:7]
	v_cvt_pk_bf16_f32 v11, v12, v13
	global_store_dwordx2 v[42:43], v[10:11], off offset:512
	v_pk_mul_f32 v[8:9], v[210:211], v[8:9]
	v_pk_add_f32 v[10:11], v[236:237], 1.0 op_sel_hi:[1,0]
	s_nop 0
	v_pk_fma_f32 v[6:7], v[10:11], v[6:7], v[224:225]
	v_pk_add_f32 v[10:11], v[238:239], 1.0 op_sel_hi:[1,0]
	v_cvt_pk_bf16_f32 v6, v6, v7
	v_pk_fma_f32 v[8:9], v[10:11], v[8:9], v[226:227]
	v_pk_mul_f32 v[2:3], v[2:3], v[212:213]
	v_cvt_pk_bf16_f32 v7, v8, v9
	global_store_dwordx2 v[42:43], v[6:7], off offset:1024
	v_pk_mul_f32 v[4:5], v[4:5], v[214:215]
	v_pk_add_f32 v[6:7], v[244:245], 1.0 op_sel_hi:[1,0]
	s_nop 0
	v_pk_fma_f32 v[2:3], v[2:3], v[6:7], v[228:229]
	v_pk_add_f32 v[6:7], v[246:247], 1.0 op_sel_hi:[1,0]
	v_cvt_pk_bf16_f32 v2, v2, v3
	v_pk_fma_f32 v[4:5], v[4:5], v[6:7], v[230:231]
	s_nop 0
	v_cvt_pk_bf16_f32 v3, v4, v5
	global_store_dwordx2 v[42:43], v[2:3], off offset:1536
	v_add_u32_e32 v2, 0x8000, v28
	v_cmp_lt_i32_e32 vcc, s94, v2
	s_or_b64 s[12:13], vcc, s[12:13]
	s_andn2_b64 exec, exec, s[12:13]
	s_cbranch_execz .LBB0_1910
